# gla_scan: K fragments for the score product read from a row-major LDS copy of the chunk K tile instead of 8 global loads per wave
# speedup vs baseline: 1.0272x; 1.0101x over previous
; #define LAS __attribute__((address_space(3)))
; DI void gla_scan(const Params& P, LAS unsigned char* lds) {
;     ...
;         GLA_LOAD(b * 2048, b * 32, qa, dc);
;         for (int n = 0; n < 32; ++n) {
;             const int row0 = b * 2048 + 64 * n;
;             LAS unsigned char* sb_ = lds + (n & 1) * GSET; LAS unsigned char* so_ = lds + ((n & 1) ^ 1) * GSET;
;             LAS bf16_t* Pm = (LAS bf16_t*)sb_; LAS bf16_t* Vt = (LAS bf16_t*)(sb_ + 9216); LAS bf16_t* St = (LAS bf16_t*)(sb_ + 13824); LAS bf16_t* KIt = (LAS bf16_t*)(sb_ + 22528);
;             LAS bf16_t* Stn = (LAS bf16_t*)(so_ + 13824);
;             if (tid < 256) { const int s = tid & 63, v8 = (tid >> 6) * 8; const bf16_t* e = (const bf16_t*)&vw;
; #pragma unroll
;                 for (int j = 0; j < 8; ++j) Vt[(v8 + j) * 72 + s] = e[j]; }
; #pragma unroll
;             for (int i = 0; i < 2; ++i) { const int idx = tid + 512 * i, s = idx & 63, d8 = (idx >> 6) * 8; const bf16_t* e = (const bf16_t*)&kw[i];
; #pragma unroll
;                 for (int j = 0; j < 8; ++j) KIt[(d8 + j) * 72 + s] = e[j]; }
; #pragma unroll
;             for (int i = 0; i < 2; ++i) { const int nb = 2 * vb + i; f32x4 sc = {0.f, 0.f, 0.f, 0.f};
; #pragma unroll
;                 for (int ks = 0; ks < 4; ++ks) sc = MFMA16(qa[ks], kbf[i][ks], sc);
; #pragma unroll
;                 for (int j = 0; j < 4; ++j) { const int t = 16 * mb + 4 * fq + j, s = 16 * nb + fr; Pm[t * 72 + s] = f2bf(s <= t ? sc[j] : 0.f); } }
;             LDS_BARRIER();
;             bf16x8 qn[4]; f32x4 dn = dc;
; #pragma unroll
;             for (int ks = 0; ks < 4; ++ks) qn[ks] = qa[ks];
;             if (n + 1 < 32) GLA_LOAD(row0 + 64, b * 32 + n + 1, qn, dn);
;             f32x4 o = {0.f, 0.f, 0.f, 0.f};
; #pragma unroll
;             for (int k2 = 0; k2 < 2; ++k2) { const bf16x8 a = *(const LAS bf16x8*)(Pm + (16 * mb + fr) * 72 + 32 * k2 + 8 * fq); const bf16x8 bb = *(const LAS bf16x8*)(Vt + (16 * vb + fr) * 72 + 32 * k2 + 8 * fq); o = MFMA16(a, bb, o); }
; #pragma unroll
;             for (int ks = 0; ks < 4; ++ks) { const bf16x8 bb = *(const LAS bf16x8*)(St + (16 * vb + fr) * 136 + 32 * ks + 8 * fq); o = MFMA16(qa[ks], bb, o); }
; #pragma unroll
;             for (int j = 0; j < 4; ++j) { const int row = row0 + 16 * mb + 4 * fq + j; OB[(size_t)row * DM + h * 256 + vs * 32 + 16 * vb + fr] = f2bf(o[j]); }
; #pragma unroll
.LBB0_1074:
	s_or_b64 exec, exec, s[16:17]
	v_add_u32_e32 v16, v144, v140
	s_waitcnt vmcnt(7)
	ds_write_b16 v16, v74 offset:63488
	ds_write_b16_d16_hi v16, v74 offset:63632
	ds_write_b16 v16, v75 offset:63776
	ds_write_b16_d16_hi v16, v75 offset:63920
	ds_write_b16 v16, v76 offset:64064
	ds_write_b16_d16_hi v16, v76 offset:64208
	ds_write_b16 v16, v77 offset:64352
	ds_write_b16_d16_hi v16, v77 offset:64496
	s_waitcnt vmcnt(6)
	ds_write_b16 v151, v70 offset:63488
	ds_write_b16_d16_hi v152, v70 offset:63488
	ds_write_b16 v153, v71 offset:63488
	ds_write_b16_d16_hi v154, v71 offset:63488
	ds_write_b16 v155, v72 offset:63488
	ds_write_b16_d16_hi v156, v72 offset:63488
	ds_write_b16 v157, v73 offset:63488
	ds_write_b16_d16_hi v158, v73 offset:63488
	v_lshrrev_b32_e32 v216, 6, v85
	v_mul_u32_u24_e32 v214, 0x110, v128
	v_lshl_add_u32 v214, v216, 4, v214
	v_add_u32_e32 v214, 0x14000, v214
	ds_write_b128 v214, v[74:77]
	ds_write_b128 v214, v[70:73] offset:128
	v_and_b32_e32 v216, 1, v216
	v_lshl_add_u32 v216, v216, 5, v82
	v_mul_u32_u24_e32 v215, 0x110, v216
	v_lshrrev_b32_e32 v216, 4, v128
	v_lshl_add_u32 v215, v216, 4, v215
	v_add_u32_e32 v215, 0x14000, v215
	s_waitcnt vmcnt(1)
	s_waitcnt lgkmcnt(0)
	s_barrier
	ds_read_b128 v[50:53], v215
	ds_read_b128 v[46:49], v215 offset:64
	ds_read_b128 v[38:41], v215 offset:128
	ds_read_b128 v[30:33], v215 offset:192
	ds_read_b128 v[26:29], v215 offset:4352
	ds_read_b128 v[20:23], v215 offset:4416
	ds_read_b128 v[12:15], v215 offset:4480
	ds_read_b128 v[8:11], v215 offset:4544
	s_waitcnt lgkmcnt(0)
	v_mfma_f32_16x16x32_bf16 v[16:19], v[66:69], v[50:53], 0
	s_lshl_b32 s15, s21, 2
	s_or_b32 s18, s15, s20
	s_ashr_i32 s19, s18, 31
	v_mfma_f32_16x16x32_bf16 v[16:19], v[58:61], v[46:49], v[16:19]
	s_lshl_b64 s[18:19], s[18:19], 17
	v_mfma_f32_16x16x32_bf16 v[16:19], v[78:81], v[38:41], v[16:19]
	v_mfma_f32_16x16x32_bf16 v[16:19], v[62:65], v[30:33], v[16:19]
	s_nop 7
	v_cvt_pk_bf16_f32 v16, v16, s0
	v_cndmask_b32_e64 v16, v16, 0, s[40:41]
	ds_write_b16 v159, v16 offset:40960
	v_cvt_pk_bf16_f32 v16, v17, s0
	v_cndmask_b32_e64 v16, v16, 0, s[42:43]
	ds_write_b16 v159, v16 offset:41104
	v_cvt_pk_bf16_f32 v16, v18, s0
	v_cndmask_b32_e64 v16, v16, 0, s[44:45]
	ds_write_b16 v159, v16 offset:41248
	v_cvt_pk_bf16_f32 v16, v19, s0
	v_cndmask_b32_e64 v16, v16, 0, s[46:47]
	ds_write_b16 v159, v16 offset:41392
	v_mfma_f32_16x16x32_bf16 v[16:19], v[66:69], v[26:29], 0
	v_mfma_f32_16x16x32_bf16 v[16:19], v[58:61], v[20:23], v[16:19]
	v_mfma_f32_16x16x32_bf16 v[12:15], v[78:81], v[12:15], v[16:19]
	v_mfma_f32_16x16x32_bf16 v[8:11], v[62:65], v[8:11], v[12:15]
	s_nop 7
	v_cvt_pk_bf16_f32 v8, v8, s0
	v_cndmask_b32_e64 v8, v8, 0, s[48:49]
	ds_write_b16 v159, v8 offset:40992
	v_cvt_pk_bf16_f32 v8, v9, s0
	v_cndmask_b32_e64 v8, v8, 0, s[50:51]
	ds_write_b16 v159, v8 offset:41136
	v_cvt_pk_bf16_f32 v8, v10, s0
	v_cndmask_b32_e64 v8, v8, 0, s[52:53]
	ds_write_b16 v159, v8 offset:41280
	v_cvt_pk_bf16_f32 v8, v11, s0
	v_cndmask_b32_e64 v8, v8, 0, s[54:55]
	ds_write_b16 v159, v8 offset:41424
	s_waitcnt lgkmcnt(0)
	s_barrier
	ds_read_b128 v[8:11], v137 offset:40960
	ds_read_b128 v[12:15], v138 offset:50176
	s_waitcnt lgkmcnt(0)
	v_mfma_f32_16x16x32_bf16 v[8:11], v[12:15], v[8:11], 0
	ds_read_b128 v[12:15], v137 offset:41024
	ds_read_b128 v[16:19], v138 offset:50240
	s_waitcnt lgkmcnt(0)
	v_mfma_f32_16x16x32_bf16 v[8:11], v[16:19], v[12:15], v[8:11]
	ds_read_b128 v[12:15], v160 offset:54784
	v_add_u32_e32 v16, v136, v142
	s_waitcnt lgkmcnt(0)
	v_mfma_f32_16x16x32_bf16 v[8:11], v[12:15], v[66:69], v[8:11]
	ds_read_b128 v[12:15], v160 offset:54848
	s_waitcnt lgkmcnt(0)
	v_mfma_f32_16x16x32_bf16 v[8:11], v[12:15], v[58:61], v[8:11]
	ds_read_b128 v[12:15], v160 offset:54912
	s_waitcnt lgkmcnt(0)
	v_mfma_f32_16x16x32_bf16 v[8:11], v[12:15], v[78:81], v[8:11]
	ds_read_b128 v[12:15], v160 offset:54976
	s_waitcnt lgkmcnt(0)
	v_mfma_f32_16x16x32_bf16 v[8:11], v[12:15], v[62:65], v[8:11]
	v_and_b32_e32 v12, 15, v187
	v_lshrrev_b32_e32 v13, 4, v187
	v_lshlrev_b32_e32 v14, 2, v13
	v_sub_u32_e32 v14, v12, v14
	v_add_u32_e32 v14, v14, v24
	v_add_u32_e32 v14, 0x7c0, v14
	v_ashrrev_i32_e32 v15, 31, v14
	v_lshlrev_b64 v[14:15], 11, v[14:15]
	v_lshlrev_b32_e32 v13, 3, v13
	v_lshlrev_b32_e32 v12, 1, v12
	v_sub_u32_e32 v12, v13, v12
	v_ashrrev_i32_e32 v13, 31, v12
	v_lshl_add_u64 v[14:15], v[116:117], 0, v[14:15]
	v_lshl_add_u64 v[14:15], v[14:15], 0, v[12:13]
	v_cvt_pk_bf16_f32 v8, v8, v9
	v_cvt_pk_bf16_f32 v9, v10, v11
	global_store_dwordx2 v[14:15], v[8:9], off
	ds_read_b128 v[8:11], v145 offset:63488
	ds_read_b128 v[12:15], v16 offset:50176
	s_waitcnt lgkmcnt(0)
	v_mfma_f32_16x16x32_bf16 v[0:3], v[8:11], v[12:15], v[0:3]
	ds_read_b128 v[12:15], v16 offset:52480
	v_lshlrev_b32_e32 v24, 2, v82
	s_waitcnt lgkmcnt(0)
	v_mfma_f32_16x16x32_bf16 v[4:7], v[8:11], v[12:15], v[4:7]
	ds_read_b128 v[8:11], v145 offset:63552
	ds_read_b128 v[12:15], v16 offset:50240
	s_load_dwordx2 s[16:17], s[0:1], 0x150
	s_waitcnt lgkmcnt(0)
	s_add_u32 s16, s16, s18
	v_mfma_f32_16x16x32_bf16 v[0:3], v[8:11], v[12:15], v[0:3]
	ds_read_b128 v[12:15], v16 offset:52544
	s_addc_u32 s17, s17, s19
	s_waitcnt lgkmcnt(0)
	v_mfma_f32_16x16x32_bf16 v[4:7], v[8:11], v[12:15], v[4:7]
	v_add_u32_e32 v10, v146, v143
	s_nop 2
	v_pk_mul_f32 v[2:3], v[36:37], v[2:3]
	v_pk_mul_f32 v[0:1], v[34:35], v[0:1]
	s_nop 1
	v_pk_mul_f32 v[6:7], v[36:37], v[6:7]
	v_pk_mul_f32 v[4:5], v[34:35], v[4:5]
	v_cvt_pk_bf16_f32 v8, v0, v1
	v_cvt_pk_bf16_f32 v9, v2, v3
	ds_write_b64 v10, v[8:9] offset:13824
	v_cvt_pk_bf16_f32 v8, v4, v5
	v_cvt_pk_bf16_f32 v9, v6, v7
	ds_write_b64 v10, v[8:9] offset:18176
	v_lshl_add_u64 v[8:9], v[114:115], 2, s[16:17]
	v_lshl_add_u64 v[8:9], v[8:9], 0, v[24:25]
	s_mov_b64 s[16:17], 0x4bf8000
	v_lshl_add_u64 v[8:9], v[8:9], 0, s[16:17]
	v_lshl_add_u64 v[10:11], v[8:9], 0, v[92:93]
	v_lshl_add_u64 v[12:13], v[8:9], 0, v[94:95]
	global_store_dword v[10:11], v0, off
	global_store_dword v[12:13], v1, off
	v_lshl_add_u64 v[0:1], v[8:9], 0, v[96:97]
	v_lshl_add_u64 v[8:9], v[8:9], 0, v[98:99]
	global_store_dword v[0:1], v2, off
	global_store_dword v[8:9], v3, off
	global_store_dword v[10:11], v4, off offset:64
	global_store_dword v[12:13], v5, off offset:64
	global_store_dword v[0:1], v6, off offset:64
	global_store_dword v[8:9], v7, off offset:64
	v_readlane_b32 s16, v255, 13
	s_waitcnt lgkmcnt(0)
	s_barrier
	v_readlane_b32 s17, v255, 14
	s_load_dword s15, s[16:17], 0x0
	s_waitcnt lgkmcnt(0)
	s_add_i32 s22, s15, s22
	s_cmpk_gt_i32 s22, 0xff
	s_cbranch_scc1 .LBB0_1094

; DI bf16_t f2bf(float f) { return (bf16_t)(pk2(f, 0.f) & 0xffffu); }
; #define LDS_BARRIER() do { asm volatile("s_waitcnt lgkmcnt(0)" ::: "memory"); __builtin_amdgcn_s_barrier(); asm volatile("" ::: "memory"); } while (0)
; #define MFMA16(a, b, c) __builtin_amdgcn_mfma_f32_16x16x32_bf16((a), (b), (c), 0, 0, 0)
; DI void gla_scan(const Params& P, LAS unsigned char* lds) {
;     ...
;             for (int i = 0; i < 2; ++i) { const int idx = tid + 512 * i, s = idx & 63, d8 = (idx >> 6) * 8; const bf16_t* e = (const bf16_t*)&kw[i];
; #pragma unroll
;                 for (int j = 0; j < 8; ++j) KIt[(d8 + j) * 72 + s] = e[j]; }
; #pragma unroll
;             for (int i = 0; i < 2; ++i) { const int nb = 2 * vb + i; f32x4 sc = {0.f, 0.f, 0.f, 0.f};
; #pragma unroll
;                 for (int ks = 0; ks < 4; ++ks) sc = MFMA16(qa[ks], kbf[i][ks], sc);
; #pragma unroll
;                 for (int j = 0; j < 4; ++j) { const int t = 16 * mb + 4 * fq + j, s = 16 * nb + fr; Pm[t * 72 + s] = f2bf(s <= t ? sc[j] : 0.f); } }
;             LDS_BARRIER();
;             bf16x8 qn[4]; f32x4 dn = dc;
; #pragma unroll
;             for (int ks = 0; ks < 4; ++ks) qn[ks] = qa[ks];
;             if (n + 1 < 32) GLA_LOAD(row0 + 64, b * 32 + n + 1, qn, dn);
.LBB0_1088:
	s_or_b64 exec, exec, s[16:17]
	v_add3_u32 v34, s29, v34, v140
	s_waitcnt vmcnt(14)
	ds_write_b16 v34, v74 offset:22528
	ds_write_b16_d16_hi v34, v74 offset:22672
	ds_write_b16 v34, v75 offset:22816
	ds_write_b16_d16_hi v34, v75 offset:22960
	ds_write_b16 v34, v76 offset:23104
	ds_write_b16_d16_hi v34, v76 offset:23248
	ds_write_b16 v34, v77 offset:23392
	ds_write_b16_d16_hi v34, v77 offset:23536
	s_waitcnt vmcnt(13)
	ds_write_b16 v34, v70 offset:31744
	ds_write_b16_d16_hi v34, v70 offset:31888
	ds_write_b16 v34, v71 offset:32032
	ds_write_b16_d16_hi v34, v71 offset:32176
	ds_write_b16 v34, v72 offset:32320
	ds_write_b16_d16_hi v34, v72 offset:32464
	ds_write_b16 v34, v73 offset:32608
	ds_write_b16_d16_hi v34, v73 offset:32752
	v_lshrrev_b32_e32 v216, 6, v85
	v_mul_u32_u24_e32 v214, 0x110, v128
	v_lshl_add_u32 v214, v216, 4, v214
	v_add_u32_e32 v214, 0x14000, v214
	ds_write_b128 v214, v[74:77]
	ds_write_b128 v214, v[70:73] offset:128
	v_and_b32_e32 v216, 1, v216
	v_lshl_add_u32 v216, v216, 5, v82
	v_mul_u32_u24_e32 v215, 0x110, v216
	v_lshrrev_b32_e32 v216, 4, v128
	v_lshl_add_u32 v215, v216, 4, v215
	v_add_u32_e32 v215, 0x14000, v215
	s_waitcnt vmcnt(1)
	s_waitcnt lgkmcnt(0)
	s_barrier
	ds_read_b128 v[50:53], v215
	ds_read_b128 v[46:49], v215 offset:64
	ds_read_b128 v[38:41], v215 offset:128
	ds_read_b128 v[30:33], v215 offset:192
	ds_read_b128 v[26:29], v215 offset:4352
	ds_read_b128 v[20:23], v215 offset:4416
	ds_read_b128 v[12:15], v215 offset:4480
	ds_read_b128 v[8:11], v215 offset:4544
	s_waitcnt lgkmcnt(0)
	v_mfma_f32_16x16x32_bf16 v[34:37], v[66:69], v[50:53], 0
	s_waitcnt vmcnt(4)
	v_mfma_f32_16x16x32_bf16 v[26:29], v[66:69], v[26:29], 0
	v_mfma_f32_16x16x32_bf16 v[34:37], v[62:65], v[46:49], v[34:37]
	s_waitcnt vmcnt(3)
	v_mfma_f32_16x16x32_bf16 v[20:23], v[62:65], v[20:23], v[26:29]
	v_mfma_f32_16x16x32_bf16 v[34:37], v[58:61], v[38:41], v[34:37]
	s_waitcnt vmcnt(2)
	v_mfma_f32_16x16x32_bf16 v[12:15], v[58:61], v[12:15], v[20:23]
	v_mfma_f32_16x16x32_bf16 v[30:33], v[54:57], v[30:33], v[34:37]
	s_waitcnt vmcnt(1)
	v_mfma_f32_16x16x32_bf16 v[8:11], v[54:57], v[8:11], v[12:15]
	s_nop 2
	v_lshlrev_b32_e32 v34, 1, v131
	s_nop 1
	v_cvt_pk_bf16_f32 v30, v30, s0
	v_cndmask_b32_e64 v30, v30, 0, s[40:41]
	v_add3_u32 v34, s29, v34, v141
	ds_write_b16 v34, v30
	v_cvt_pk_bf16_f32 v8, v8, s0
	v_cndmask_b32_e64 v8, v8, 0, s[48:49]
	v_cvt_pk_bf16_f32 v30, v31, s0
	ds_write_b16 v34, v8 offset:32
	v_cvt_pk_bf16_f32 v8, v9, s0
	v_cndmask_b32_e64 v30, v30, 0, s[42:43]
	v_cndmask_b32_e64 v8, v8, 0, s[50:51]
	ds_write_b16 v34, v30 offset:144
	v_cvt_pk_bf16_f32 v30, v32, s0
	ds_write_b16 v34, v8 offset:176
	v_cvt_pk_bf16_f32 v8, v10, s0
	v_cndmask_b32_e64 v30, v30, 0, s[44:45]
	v_cndmask_b32_e64 v8, v8, 0, s[52:53]
	ds_write_b16 v34, v30 offset:288
	v_cvt_pk_bf16_f32 v30, v33, s0
	ds_write_b16 v34, v8 offset:320
	v_cvt_pk_bf16_f32 v8, v11, s0
	v_cndmask_b32_e64 v30, v30, 0, s[46:47]
	v_cndmask_b32_e64 v8, v8, 0, s[54:55]
	ds_write_b16 v34, v30 offset:432
	ds_write_b16 v34, v8 offset:464
	s_waitcnt lgkmcnt(0)
	s_barrier
	v_add_u32_e32 v8, s15, v111
	v_ashrrev_i32_e32 v9, 31, v8
	s_and_saveexec_b64 s[16:17], vcc
	s_cbranch_execz .LBB0_1090
	v_mad_i64_i32 v[10:11], s[56:57], v8, s87, v[122:123]
	global_load_dwordx4 v[16:19], v[10:11], off offset:2048
; #define LAS __attribute__((address_space(3)))
; DI unsigned pk2(float lo, float hi) { const f32x2v v = {lo, hi}; const bf16x2v b = __builtin_convertvector(v, bf16x2v); return __builtin_bit_cast(unsigned, b); }
; DI bf16_t f2bf(float f) { return (bf16_t)(pk2(f, 0.f) & 0xffffu); }
; #define MFMA16(a, b, c) __builtin_amdgcn_mfma_f32_16x16x32_bf16((a), (b), (c), 0, 0, 0)
; DI void gla_scan(const Params& P, LAS unsigned char* lds) {
;     ...
;             if (n + 1 < 32) GLA_LOAD(row0 + 64, b * 32 + n + 1, qn, dn);
;             f32x4 o = {0.f, 0.f, 0.f, 0.f};
; #pragma unroll
;             for (int k2 = 0; k2 < 2; ++k2) { const bf16x8 a = *(const LAS bf16x8*)(Pm + (16 * mb + fr) * 72 + 32 * k2 + 8 * fq); const bf16x8 bb = *(const LAS bf16x8*)(Vt + (16 * vb + fr) * 72 + 32 * k2 + 8 * fq); o = MFMA16(a, bb, o); }
; #pragma unroll
;             for (int ks = 0; ks < 4; ++ks) { const bf16x8 bb = *(const LAS bf16x8*)(St + (16 * vb + fr) * 136 + 32 * ks + 8 * fq); o = MFMA16(qa[ks], bb, o); }
; #pragma unroll
;             for (int j = 0; j < 4; ++j) { const int row = row0 + 16 * mb + 4 * fq + j; OB[(size_t)row * DM + h * 256 + vs * 32 + 16 * vb + fr] = f2bf(o[j]); }
; #pragma unroll
;             for (int k2 = 0; k2 < 2; ++k2) { const bf16x8 a = *(const LAS bf16x8*)(KIt + (16 * wid + fr) * 72 + 32 * k2 + 8 * fq);
; #pragma unroll
;                 for (int v2 = 0; v2 < 2; ++v2) { const bf16x8 bb = *(const LAS bf16x8*)(Vt + (16 * v2 + fr) * 72 + 32 * k2 + 8 * fq); Sacc[v2] = MFMA16(a, bb, Sacc[v2]); } }
;             Sacc[0] *= dc; Sacc[1] *= dc;
; #pragma unroll
;             for (int v2 = 0; v2 < 2; ++v2) { u32x2 w; w.x = pk2(Sacc[v2][0], Sacc[v2][1]); w.y = pk2(Sacc[v2][2], Sacc[v2][3]); *(LAS u32x2*)(Stn + (16 * v2 + fr) * 136 + 16 * wid + 4 * fq) = w; }
; #pragma unroll
;             for (int ks = 0; ks < 4; ++ks) qa[ks] = qn[ks];
;             dc = dn;
.LBB0_1090:
	s_or_b64 exec, exec, s[16:17]
	v_lshlrev_b64 v[8:9], 10, v[8:9]
	v_lshl_add_u64 v[8:9], v[124:125], 0, v[8:9]
	v_add_u32_e32 v10, s15, v109
	global_load_dwordx4 v[74:77], v[8:9], off
	global_load_dwordx4 v[70:73], v[8:9], off offset:128
	v_add_u32_e32 v8, 64, v10
	v_ashrrev_i32_e32 v9, 31, v8
	v_lshlrev_b64 v[8:9], 10, v[8:9]
	v_lshl_add_u64 v[8:9], v[118:119], 0, v[8:9]
	v_lshl_add_u32 v113, v84, 1, s29
	s_nop 0
	s_nop 0
	s_nop 0
	s_nop 0
	v_add_u32_e32 v8, 0x50, v10
	v_add_u32_e32 v10, v113, v132
	ds_read_b128 v[34:37], v10
	v_add_u32_e32 v161, v113, v133
	v_ashrrev_i32_e32 v9, 31, v8
	ds_read_b128 v[78:81], v161 offset:9216
	ds_read_b128 v[162:165], v10 offset:64
	v_lshlrev_b64 v[8:9], 10, v[8:9]
	v_lshl_add_u64 v[8:9], v[118:119], 0, v[8:9]
	s_nop 0
	s_nop 0
	s_nop 0
	s_nop 0
	s_nop 0
	ds_read_b128 v[168:171], v161 offset:9280
	s_waitcnt lgkmcnt(2)
	v_mfma_f32_16x16x32_bf16 v[78:81], v[78:81], v[34:37], 0
	v_add3_u32 v161, s29, v134, v90
	ds_read_b128 v[172:175], v161 offset:13824
	global_load_dwordx4 v[34:37], v[126:127], off
	s_waitcnt lgkmcnt(1)
	v_mfma_f32_16x16x32_bf16 v[78:81], v[168:171], v[162:165], v[78:81]
	ds_read_b128 v[162:165], v161 offset:13888
	v_add_u32_e32 v168, s15, v107
	v_ashrrev_i32_e32 v169, 31, v168
	s_waitcnt lgkmcnt(1)
	v_mfma_f32_16x16x32_bf16 v[66:69], v[172:175], v[66:69], v[78:81]
	v_add_u32_e32 v212, s15, v24
	v_ashrrev_i32_e32 v213, 31, v212
	s_xor_b32 s16, s19, 1
	v_lshlrev_b64 v[78:79], 10, v[168:169]
	ds_read_b128 v[168:171], v161 offset:13952
	s_waitcnt lgkmcnt(1)
	v_mfma_f32_16x16x32_bf16 v[66:69], v[162:165], v[62:65], v[66:69]
	v_lshl_add_u64 v[172:173], v[120:121], 0, v[78:79]
	global_load_dwordx4 v[62:65], v[172:173], off offset:192
	global_load_dwordx4 v[78:81], v[172:173], off offset:128
	ds_read_b128 v[162:165], v161 offset:14016
	s_waitcnt lgkmcnt(1)
	v_mfma_f32_16x16x32_bf16 v[168:171], v[168:171], v[58:61], v[66:69]
	global_load_dwordx4 v[58:61], v[172:173], off offset:64
	s_nop 1
	global_load_dwordx4 v[66:69], v[172:173], off
	s_mul_i32 s16, s16, 0xa000
	s_add_i32 s15, s15, 64
	s_waitcnt lgkmcnt(0)
	v_mfma_f32_16x16x32_bf16 v[54:57], v[162:165], v[54:57], v[168:171]
	v_and_b32_e32 v164, 15, v187
	v_lshrrev_b32_e32 v165, 4, v187
	v_lshlrev_b32_e32 v161, 2, v165
	v_sub_u32_e32 v161, v164, v161
	v_add_u32_e32 v212, v212, v161
	v_ashrrev_i32_e32 v213, 31, v212
	v_lshlrev_b64 v[162:163], 11, v[212:213]
	v_lshl_add_u64 v[162:163], v[116:117], 0, v[162:163]
	v_lshlrev_b32_e32 v165, 3, v165
	v_lshlrev_b32_e32 v164, 1, v164
	v_sub_u32_e32 v164, v165, v164
	v_ashrrev_i32_e32 v165, 31, v164
	v_lshl_add_u64 v[162:163], v[162:163], 0, v[164:165]
	s_add_i32 s18, s18, 1
	s_cmpk_eq_i32 s15, 0x7c0
	s_nop 3
	v_cvt_pk_bf16_f32 v54, v54, v55
	v_cvt_pk_bf16_f32 v55, v56, v57
	global_store_dwordx2 v[162:163], v[54:55], off
	s_nop 0
	s_nop 0
	s_nop 0
	s_nop 0
	s_nop 0
	s_nop 0
	v_add_u32_e32 v161, v113, v135
	ds_read_b128 v[162:165], v161 offset:22528
	v_add_u32_e32 v113, v113, v142
	ds_read_b128 v[168:171], v113 offset:9216
	ds_read_b128 v[172:175], v113 offset:11520
	ds_read_b128 v[176:179], v161 offset:22592
	ds_read_b128 v[180:183], v113 offset:9280
	s_waitcnt lgkmcnt(3)
	v_mfma_f32_16x16x32_bf16 v[0:3], v[162:165], v[168:171], v[0:3]
	ds_read_b128 v[168:171], v113 offset:11584
	s_nop 0
	s_nop 0
	s_waitcnt lgkmcnt(3)
	v_mfma_f32_16x16x32_bf16 v[4:7], v[162:165], v[172:175], v[4:7]
	s_nop 0
	s_nop 0
	s_nop 0
	s_waitcnt lgkmcnt(1)
	v_mfma_f32_16x16x32_bf16 v[0:3], v[176:179], v[180:183], v[0:3]
	s_nop 0
	s_nop 0
	s_nop 0
	s_waitcnt lgkmcnt(0)
	v_mfma_f32_16x16x32_bf16 v[4:7], v[176:179], v[168:171], v[4:7]
	s_nop 0
	s_waitcnt vmcnt(8)
	s_nop 0
	v_pk_mul_f32 v[2:3], v[44:45], v[2:3]
	v_pk_mul_f32 v[0:1], v[42:43], v[0:1]
	s_nop 0
	s_nop 0
	s_nop 0
	v_pk_mul_f32 v[6:7], v[44:45], v[6:7]
	v_pk_mul_f32 v[4:5], v[42:43], v[4:5]
	v_cvt_pk_bf16_f32 v42, v0, v1
	v_cvt_pk_bf16_f32 v43, v2, v3
	v_add3_u32 v44, v146, s16, v143
	s_mov_b64 s[16:17], 0x800
	ds_write_b64 v44, v[42:43] offset:13824
	v_cvt_pk_bf16_f32 v42, v4, v5
	v_cvt_pk_bf16_f32 v43, v6, v7
	v_lshl_add_u64 v[126:127], v[126:127], 0, s[16:17]
	s_nop 0
	ds_write_b64 v44, v[42:43] offset:18176
	s_cbranch_scc1 .LBB0_1092
	s_waitcnt vmcnt(5)
	v_mov_b64_e32 v[44:45], v[36:37]
	s_waitcnt vmcnt(4)
	v_mov_b64_e32 v[54:55], v[62:63]
	v_mov_b64_e32 v[42:43], v[34:35]
	v_mov_b64_e32 v[56:57], v[64:65]
	s_waitcnt vmcnt(2)
	v_mov_b32_e32 v62, v58
	v_mov_b32_e32 v63, v59
	v_mov_b32_e32 v64, v60
	v_mov_b32_e32 v65, v61
	v_mov_b32_e32 v58, v78
	v_mov_b32_e32 v59, v79
	v_mov_b32_e32 v60, v80
	v_mov_b32_e32 v61, v81
	s_branch .LBB0_1086
